# mla_c: wave reductions via DPP adds + one bpermute + permlane32 swap instead of six bpermute round trips
# baseline (speedup 1.0000x reference)
; __device__ __forceinline__ unsigned pk2(float lo, float hi) { f32x2_t v = {lo, hi}; bf16x2_t b = __builtin_convertvector(v, bf16x2_t); return __builtin_bit_cast(unsigned, b); }
; __device__ __forceinline__ float bflo(unsigned u) { return __uint_as_float(u << 16); }
; __device__ __forceinline__ float bfhi(unsigned u) { return __uint_as_float(u & 0xffff0000u); }
; __device__ __forceinline__ float wave_sum(float v) {
; #pragma unroll
;     for (int o = 1; o < 64; o <<= 1) v += __shfl_xor(v, o);
;     return v;
; }
; __device__ __forceinline__ void mla_c(CArgs a, int jl, int gw, int NGW, int lane) {
;     ...
;     for (int m = gw; m < NTOK; m += NGW) {
;         const bf16_t* d = DOWN + (size_t)m * 768;
;         unsigned qv[3]; float ss = 0.f;
; #pragma unroll
;         for (int j = 0; j < 3; ++j) { qv[j] = *(const unsigned*)(d + 2 * lane + 128 * j); const float x0 = bflo(qv[j]), x1 = bfhi(qv[j]); ss += x0 * x0 + x1 * x1; }
;         const float rq = rsqrtf(wave_sum(ss) * (1.f / 384.f) + EPS);
; #pragma unroll
;         for (int j = 0; j < 3; ++j) { const int c = 2 * lane + 128 * j; *(unsigned*)(CQ + (size_t)m * 384 + c) = pk2(bflo(qv[j]) * rq * qn[c], bfhi(qv[j]) * rq * qn[c + 1]); }
;         const u32x2 kv = *(const u32x2*)(d + 384 + 4 * lane);
;         const float k0 = bflo(kv.x), k1 = bfhi(kv.x), k2 = bflo(kv.y), k3 = bfhi(kv.y);
;         const float rk = rsqrtf(wave_sum((k0 * k0 + k1 * k1) + (k2 * k2 + k3 * k3)) * (1.f / 256.f) + EPS);
;         const f32x4 g = *(const f32x4*)(kvn + 4 * lane);
;         u32x2 w; w.x = pk2(k0 * rk * g[0], k1 * rk * g[1]); w.y = pk2(k2 * rk * g[2], k3 * rk * g[3]);
;         *(u32x2*)(CKV + (size_t)m * 256 + 4 * lane) = w;
;         const float x = __uint_as_float(((unsigned)d[640 + lane]) << 16);
;         const float other = __shfl_xor(x, 32);
;         const int pos = tok_pos(m), i = lane & 31;
;         const float c = COS[pos * 32 + i], s = SIN[pos * 32 + i];
;         const float y = (lane < 32) ? (x * c - other * s) : (x * c + other * s);
;         KR[(size_t)m * 64 + lane] = (bf16_t)(pk2(y, 0.f) & 0xffffu);
;     }
.LBB0_371:
	v_lshl_add_u64 v[24:25], s[2:3], 0, v[16:17]
	v_add_co_u32_e32 v24, vcc, 0xd800000, v24
	global_load_dwordx2 v[30:31], v[4:5], off
	global_load_dwordx2 v[36:37], v[4:5], off offset:512
	v_addc_co_u32_e32 v25, vcc, 0, v25, vcc
	global_load_dword v27, v[24:25], off
	global_load_dword v29, v[24:25], off offset:256
	v_lshl_add_u64 v[32:33], s[2:3], 0, v[10:11]
	global_load_dword v25, v[24:25], off offset:512
	s_cmpk_lt_i32 s48, 0x4000
	s_movk_i32 s7, 0x7ff
	s_cselect_b32 s7, s7, 0x1fff
	s_and_b32 s7, s7, s48
	global_load_dwordx2 v[42:43], v[4:5], off offset:1024
	v_lshl_add_u64 v[46:47], s[2:3], 0, v[12:13]
	v_lshl_add_u64 v[54:55], s[2:3], 0, v[14:15]
	v_lshl_or_b32 v56, s7, 7, v0
	global_load_dwordx2 v[44:45], v[46:47], off
	global_load_dwordx4 v[48:51], v[2:3], off
	global_load_ushort v52, v[54:55], off
	global_load_dword v57, v56, s[4:5]
	global_load_dword v58, v56, s[16:17]
	s_mov_b32 s6, 0x15800000
	v_lshl_add_u64 v[10:11], v[10:11], 0, s[64:65]
	v_lshl_add_u64 v[16:17], v[16:17], 0, s[66:67]
	s_waitcnt vmcnt(8)
	v_lshlrev_b32_e32 v26, 16, v27
	v_and_b32_e32 v27, 0xffff0000, v27
	s_waitcnt vmcnt(7)
	v_lshlrev_b32_e32 v28, 16, v29
	s_waitcnt vmcnt(6)
	v_lshlrev_b32_e32 v24, 16, v25
	v_and_b32_e32 v25, 0xffff0000, v25
	v_and_b32_e32 v29, 0xffff0000, v29
	v_mov_b32_e32 v40, v27
	v_mov_b32_e32 v41, v25
	v_pk_mul_f32 v[34:35], v[28:29], v[28:29]
	v_mov_b32_e32 v38, v26
	v_mov_b32_e32 v39, v24
	v_pk_mul_f32 v[40:41], v[40:41], v[40:41]
	v_add_f32_e32 v34, v34, v35
	v_pk_fma_f32 v[38:39], v[38:39], v[38:39], v[40:41]
	s_nop 0
	v_add_f32_e32 v34, v38, v34
	v_add_f32_e32 v34, v34, v39
	s_nop 1
	v_add_f32_dpp v34, v34, v34 quad_perm:[1,0,3,2] row_mask:0xf bank_mask:0xf
	s_nop 1
	v_add_f32_dpp v34, v34, v34 quad_perm:[2,3,0,1] row_mask:0xf bank_mask:0xf
	s_nop 1
	v_add_f32_dpp v34, v34, v34 row_half_mirror row_mask:0xf bank_mask:0xf
	s_nop 1
	v_add_f32_dpp v34, v34, v34 row_mirror row_mask:0xf bank_mask:0xf
	ds_bpermute_b32 v35, v22, v34
	s_waitcnt lgkmcnt(0)
	v_add_f32_e32 v34, v34, v35
	v_mov_b32_e32 v35, v34
	s_nop 1
	v_permlane32_swap_b32_e32 v34, v35
	v_add_f32_e32 v34, v34, v35
	v_fmamk_f32 v34, v34, 0x3b2aaaab, v201
	v_cmp_gt_f32_e32 vcc, s55, v34
	v_mul_f32_e32 v35, 0x4b800000, v34
	s_nop 0
	v_cndmask_b32_e32 v34, v34, v35, vcc
	v_rsq_f32_e32 v34, v34
	s_nop 0
	v_mul_f32_e32 v35, 0x45800000, v34
	v_cndmask_b32_e32 v34, v34, v35, vcc
	v_pk_mul_f32 v[26:27], v[34:35], v[26:27] op_sel_hi:[0,1]
	v_pk_mul_f32 v[26:27], v[30:31], v[26:27]
	v_pk_mul_f32 v[28:29], v[34:35], v[28:29] op_sel_hi:[0,1]
	v_cvt_pk_bf16_f32 v30, v26, v27
	v_add_co_u32_e32 v26, vcc, s6, v32
	v_pk_mul_f32 v[28:29], v[36:37], v[28:29]
	s_nop 0
	v_addc_co_u32_e32 v27, vcc, 0, v33, vcc
	v_cvt_pk_bf16_f32 v28, v28, v29
	global_store_dword v[26:27], v28, off offset:256
	v_pk_mul_f32 v[24:25], v[34:35], v[24:25] op_sel_hi:[0,1]
	global_store_dword v[26:27], v30, off
	s_add_i32 s48, s48, s54
	s_cmpk_gt_i32 s48, 0x7fff
	s_waitcnt vmcnt(7)
	v_pk_mul_f32 v[24:25], v[42:43], v[24:25]
	s_nop 0
	v_cvt_pk_bf16_f32 v24, v24, v25
	global_store_dword v[26:27], v24, off offset:512
	v_lshl_add_u64 v[12:13], v[12:13], 0, s[66:67]
	s_waitcnt vmcnt(7)
	v_and_b32_e32 v31, 0xffff0000, v45
	v_and_b32_e32 v33, 0xffff0000, v44
	v_lshlrev_b32_e32 v30, 16, v45
	v_lshlrev_b32_e32 v32, 16, v44
	v_mov_b32_e32 v34, v33
	v_mov_b32_e32 v35, v31
	v_mov_b32_e32 v28, v32
	v_mov_b32_e32 v29, v30
	v_pk_mul_f32 v[34:35], v[34:35], v[34:35]
	s_nop 0
	v_pk_fma_f32 v[28:29], v[28:29], v[28:29], v[34:35]
	s_nop 0
	v_add_f32_e32 v28, v28, v29
	s_nop 1
	v_add_f32_dpp v28, v28, v28 quad_perm:[1,0,3,2] row_mask:0xf bank_mask:0xf
	s_nop 1
	v_add_f32_dpp v28, v28, v28 quad_perm:[2,3,0,1] row_mask:0xf bank_mask:0xf
	s_nop 1
	v_add_f32_dpp v28, v28, v28 row_half_mirror row_mask:0xf bank_mask:0xf
	s_nop 1
	v_add_f32_dpp v28, v28, v28 row_mirror row_mask:0xf bank_mask:0xf
	ds_bpermute_b32 v29, v22, v28
	s_waitcnt lgkmcnt(0)
	v_add_f32_e32 v28, v28, v29
	v_mov_b32_e32 v29, v28
	s_nop 1
	v_permlane32_swap_b32_e32 v28, v29
	v_add_f32_e32 v28, v28, v29
	v_fmamk_f32 v28, v28, 0x3b800000, v201
	v_cmp_gt_f32_e32 vcc, s55, v28
	v_mul_f32_e32 v29, 0x4b800000, v28
	s_nop 0
	v_cndmask_b32_e32 v28, v28, v29, vcc
	v_rsq_f32_e32 v28, v28
	s_nop 0
	v_mul_f32_e32 v29, 0x45800000, v28
	v_cndmask_b32_e32 v28, v28, v29, vcc
	v_pk_mul_f32 v[32:33], v[28:29], v[32:33] op_sel_hi:[0,1]
	v_pk_mul_f32 v[28:29], v[28:29], v[30:31] op_sel_hi:[0,1]
	s_waitcnt vmcnt(6)
	v_pk_mul_f32 v[24:25], v[48:49], v[32:33]
	v_pk_mul_f32 v[26:27], v[50:51], v[28:29]
	v_cvt_pk_bf16_f32 v24, v24, v25
	v_cvt_pk_bf16_f32 v25, v26, v27
	v_lshl_add_u64 v[26:27], s[2:3], 0, v[8:9]
	global_store_dwordx2 v[26:27], v[24:25], off
	v_lshl_add_u64 v[8:9], v[8:9], 0, s[72:73]
	v_lshl_add_u64 v[14:15], v[14:15], 0, s[66:67]
	s_waitcnt vmcnt(6)
	v_lshlrev_b32_e32 v24, 16, v52
	ds_bpermute_b32 v25, v23, v24
	s_waitcnt vmcnt(4) lgkmcnt(0)
	v_mul_f32_e32 v25, v58, v25
	v_cndmask_b32_e64 v25, v25, -v25, s[38:39]
	v_fmac_f32_e32 v25, v57, v24
	v_cvt_pk_bf16_f32 v26, v25, s0
	v_lshl_add_u64 v[24:25], s[2:3], 0, v[6:7]
	v_lshl_add_u64 v[6:7], v[6:7], 0, s[68:69]
	global_store_short v[24:25], v26, off
	s_cbranch_scc0 .LBB0_371
